# attention K/V tile loads with sc0 (L1 bypass; each line is read once per CU)
# speedup vs baseline: 1.0082x; 1.0021x over previous
; __device__ void attn_item(const Params& p, char* lds, int bh, int qi) {
;     ...
;   float mref = 0.f, lsum = 0.f;
;   bool first = true;
;   const int nsteps = (qi + 1) * 4;
;   const int skey = tid >> 3, sch = tid & 7;
;   u32x4 rk, rv;
;   auto gload = [&](int s) {
;     const int jb = qi - (s >> 2), sub = s & 3, key0 = jb * 256 + sub * 64;
;     rk = *(const u32x4*)(Kg + (size_t)(key0 + skey) * 64 + sch * 8);
;     rv = *(const u32x4*)(Vg + (size_t)skey * SEQ + key0 + sch * 8);
;   };
;   auto swrite = [&](int buf) {
;     *(u32x4*)(Ks + buf * 64 * LD + skey * LD + sch * 8) = rk;
;     u16* vd = Vs + buf * 64 * LD + skey * LD + 16 * (sch >> 1) + 4 * (sch & 1);
;     u32x2 a, b; a.x = rv.x; a.y = rv.y; b.x = rv.z; b.y = rv.w;
;     *(u32x2*)(vd) = a;
;     *(u32x2*)(vd + 8) = b;
;   };
;   gload(0); swrite(0);
;   __syncthreads();
.LBB0_414:
	s_lshl_b32 s5, s22, 18
	s_lshl_b32 s5, s5, 1
	s_add_u32 s18, s10, s5
	v_or_b32_e32 v2, s4, v240
	v_mov_b32_e32 v3, v95
	v_lshl_add_u64 v[18:19], v[96:97], 0, s[6:7]
	s_mov_b32 s5, s7
	s_addc_u32 s19, s11, 0
	v_lshlrev_b64 v[2:3], 7, v[2:3]
	v_mov_b32_e32 v107, v95
	v_lshl_add_u64 v[4:5], s[4:5], 1, v[18:19]
	v_lshl_add_u64 v[2:3], s[18:19], 0, v[2:3]
	v_lshl_add_u64 v[4:5], v[4:5], 0, v[106:107]
	v_lshl_add_u64 v[2:3], v[2:3], 0, v[106:107]
	global_load_dwordx4 v[86:89], v[4:5], off sc0
	global_load_dwordx4 v[82:85], v[2:3], off sc0
	s_mov_b32 s94, 1
	v_cmp_lt_i32_e32 vcc, v156, v157
	s_nop 1
	v_cndmask_b32_e32 v192, v1, v156, vcc
	v_lshlrev_b32_e32 v192, 2, v192
	v_mov_b32_e32 v16, v95
	v_mov_b32_e32 v17, v95
	v_mov_b32_e32 v2, v95
	v_mov_b32_e32 v3, v95
	v_mov_b32_e32 v4, v95
	v_mov_b32_e32 v5, v95
	v_mov_b32_e32 v6, v95
	v_mov_b32_e32 v7, v95
	v_mov_b32_e32 v8, v95
	v_mov_b32_e32 v9, v95
	v_mov_b32_e32 v10, v95
	v_mov_b32_e32 v11, v95
	v_mov_b32_e32 v12, v95
	v_mov_b32_e32 v13, v95
	v_mov_b32_e32 v14, v95
	v_mov_b32_e32 v15, v95
	v_lshl_add_u64 v[108:109], v[18:19], 0, v[106:107]
	v_mov_b64_e32 v[32:33], v[16:17]
	s_lshl_b32 s38, s37, 2
	v_add_u32_e32 v34, 0x4800, v117
	s_mov_b32 s6, 0
	s_mov_b64 s[14:15], -1
	v_mov_b32_e32 v126, 0
	s_mov_b32 s26, 0
	v_mov_b64_e32 v[30:31], v[14:15]
	v_mov_b64_e32 v[28:29], v[12:13]
	v_mov_b64_e32 v[26:27], v[10:11]
	v_mov_b64_e32 v[24:25], v[8:9]
	v_mov_b64_e32 v[22:23], v[6:7]
	v_mov_b64_e32 v[20:21], v[4:5]
	v_mov_b64_e32 v[18:19], v[2:3]
	s_add_i32 s38, s38, 4
	v_lshl_add_u64 v[110:111], s[18:19], 0, v[106:107]
	v_mov_b32_e32 v107, 0
	s_waitcnt vmcnt(1)
	ds_write2_b64 v34, v[86:87], v[88:89] offset1:2
	s_waitcnt vmcnt(0)
	ds_write_b128 v116, v[82:85]
	s_lshl_b32 s20, s37, 8
	s_or_b32 s20, s20, 64
	v_add_u32_e32 v34, s20, v240
	v_ashrrev_i32_e32 v35, 31, v34
	v_lshlrev_b64 v[34:35], 7, v[34:35]
	v_lshl_add_u64 v[34:35], v[110:111], 0, v[34:35]
	s_ashr_i32 s21, s20, 31
	global_load_dwordx4 v[82:85], v[34:35], off sc0
	v_lshl_add_u64 v[34:35], s[20:21], 1, v[108:109]
	global_load_dwordx4 v[86:89], v[34:35], off sc0
	s_waitcnt lgkmcnt(0)
	s_barrier

; __device__ void attn_item(const Params& p, char* lds, int bh, int qi) {
;     ...
;   auto gload = [&](int s) {
;     const int jb = qi - (s >> 2), sub = s & 3, key0 = jb * 256 + sub * 64;
;     rk = *(const u32x4*)(Kg + (size_t)(key0 + skey) * 64 + sch * 8);
;     rv = *(const u32x4*)(Vg + (size_t)skey * SEQ + key0 + sch * 8);
;   };
;   auto swrite = [&](int buf) {
;     *(u32x4*)(Ks + buf * 64 * LD + skey * LD + sch * 8) = rk;
;     u16* vd = Vs + buf * 64 * LD + skey * LD + 16 * (sch >> 1) + 4 * (sch & 1);
;     u32x2 a, b; a.x = rv.x; a.y = rv.y; b.x = rv.z; b.y = rv.w;
;     *(u32x2*)(vd) = a;
;     *(u32x2*)(vd + 8) = b;
;   };
.LBB0_424:
	s_bitcmp1_b32 s39, 0
	s_cselect_b32 s14, 0x2400, 0
	v_add_u32_e32 v34, s14, v116
	v_add_u32_e32 v35, s14, v117
	s_waitcnt vmcnt(1)
	ds_write_b128 v34, v[82:85]
	v_add_u32_e32 v34, 0x4800, v35
	s_waitcnt vmcnt(0)
	ds_write2_b64 v34, v[86:87], v[88:89] offset1:2
	s_add_i32 s14, s39, 1
	s_cmp_ge_u32 s14, s38
	s_cbranch_scc1 .Lattn_nogl
	s_lshr_b32 s20, s14, 2
	s_sub_i32 s20, s37, s20
	s_lshl_b32 s20, s20, 8
	s_lshl_b32 s21, s14, 6
	s_and_b32 s21, s21, 0xc0
	s_or_b32 s20, s20, s21
	v_add_u32_e32 v34, s20, v240
	v_ashrrev_i32_e32 v35, 31, v34
	v_lshlrev_b64 v[34:35], 7, v[34:35]
	v_lshl_add_u64 v[34:35], v[110:111], 0, v[34:35]
	s_ashr_i32 s21, s20, 31
	global_load_dwordx4 v[82:85], v[34:35], off sc0
	v_lshl_add_u64 v[34:35], s[20:21], 1, v[108:109]
	global_load_dwordx4 v[86:89], v[34:35], off sc0
